# v97 stack + conv FMA-loop row addresses derived by constant 64-bit adds (one carry pair instead of eight) + P9 EpiFinal row-sum exchange via v_permlane16/32_swap instead of ds_bpermute
# baseline (speedup 1.0000x reference)
; #define LAS __attribute__((address_space(3)))
; __global__ void __launch_bounds__(NWAVES * 64, 2) mk_fwd(Args args) {
;     ...
;             const int cp = tid & 255, th = tid >> 8;
;             f32x2 w[31];
; #pragma unroll
;             for (int j = 0; j < 31; ++j) w[j] = *(const f32x2*)(conv_w + j * 512 + 2 * cp);
;             const f32x2 cb = *(const f32x2*)(conv_b + 2 * cp);
;             LAS float* yt = (LAS float*)lds;
;             f32x4 lg0 = *(const f32x4*)(ln_g + 4 * lane), lg1 = *(const f32x4*)(ln_g + 256 + 4 * lane), lb0 = *(const f32x4*)(ln_b + 4 * lane), lb1 = *(const f32x4*)(ln_b + 256 + 4 * lane);
;     ...
;             for (int repc = 0; repc < REPC; ++repc)
;             for (int kt = 0, tile = (G == 256) ? 64 * (vcu >> 5) + (vcu & 31) : vcu; tile < T / 64; ++kt, tile = (G == 256) ? ((kt < 2) ? 64 * (vcu >> 5) + 32 * kt + (vcu & 31) : T) : tile + G) {
.LBB0_352:
	s_lshl_b32 s4, s73, 1
	s_andn2_b32 s4, s4, 63
	s_and_b32 s5, s73, 31
	s_or_b32 s4, s4, s5
	s_and_b64 s[6:7], s[50:51], exec
	s_cselect_b32 s6, s4, s73
	s_cmpk_lt_i32 s6, 0x200
	s_cbranch_scc0 .LBB0_361
	v_lshlrev_b32_e32 v0, 1, v200
	v_and_b32_e32 v20, 0x1fe, v0
	v_mov_b32_e32 v80, 0
	v_lshlrev_b32_e32 v0, 2, v20
	v_mov_b32_e32 v1, v80
	v_lshl_add_u64 v[2:3], s[18:19], 0, v[0:1]
	v_add_co_u32_e32 v4, vcc, 0x1000, v2
	v_lshl_add_u64 v[0:1], s[16:17], 0, v[0:1]
	s_nop 0
	v_addc_co_u32_e32 v5, vcc, 0, v3, vcc
	flat_load_dwordx2 v[82:83], v[2:3]
	flat_load_dwordx2 v[84:85], v[2:3] offset:2048
	flat_load_dwordx2 v[86:87], v[4:5]
	flat_load_dwordx2 v[88:89], v[4:5] offset:2048
	v_add_co_u32_e32 v4, vcc, 0x2000, v2
	v_mov_b32_e32 v17, v80
	s_nop 0
	v_addc_co_u32_e32 v5, vcc, 0, v3, vcc
	v_add_co_u32_e32 v6, vcc, 0x3000, v2
	s_ashr_i32 s5, s72, 6
	s_nop 0
	v_addc_co_u32_e32 v7, vcc, 0, v3, vcc
	flat_load_dwordx2 v[90:91], v[4:5]
	flat_load_dwordx2 v[92:93], v[4:5] offset:2048
	flat_load_dwordx2 v[94:95], v[6:7]
	flat_load_dwordx2 v[96:97], v[6:7] offset:2048
	v_add_co_u32_e32 v4, vcc, 0x4000, v2
	s_movk_i32 s7, 0x1000
	s_nop 0
	v_addc_co_u32_e32 v5, vcc, 0, v3, vcc
	v_add_co_u32_e32 v6, vcc, 0x5000, v2
	s_movk_i32 s8, 0x2000
	s_nop 0
	v_addc_co_u32_e32 v7, vcc, 0, v3, vcc
	flat_load_dwordx2 v[98:99], v[4:5]
	s_nop 0
	flat_load_dwordx2 v[100:101], v[4:5] offset:2048
	flat_load_dwordx2 v[102:103], v[6:7]
	flat_load_dwordx2 v[104:105], v[6:7] offset:2048
	v_add_co_u32_e32 v4, vcc, 0x6000, v2
	s_movk_i32 s9, 0x3000
	s_nop 0
	v_addc_co_u32_e32 v5, vcc, 0, v3, vcc
	v_add_co_u32_e32 v6, vcc, 0x7000, v2
	v_mov_b32_e32 v176, 0x358637bd
	s_nop 0
	v_addc_co_u32_e32 v7, vcc, 0, v3, vcc
	flat_load_dwordx2 v[106:107], v[4:5]
	flat_load_dwordx2 v[108:109], v[4:5] offset:2048
	flat_load_dwordx2 v[110:111], v[6:7]
	flat_load_dwordx2 v[112:113], v[6:7] offset:2048
	v_add_co_u32_e32 v4, vcc, 0x8000, v2
	v_mov_b32_e32 v177, 0x260
	s_nop 0
	v_addc_co_u32_e32 v5, vcc, 0, v3, vcc
	v_add_co_u32_e32 v6, vcc, 0x9000, v2
	s_nop 1
	v_addc_co_u32_e32 v7, vcc, 0, v3, vcc
	flat_load_dwordx2 v[114:115], v[4:5]
	flat_load_dwordx2 v[116:117], v[4:5] offset:2048
	flat_load_dwordx2 v[118:119], v[6:7]
	flat_load_dwordx2 v[120:121], v[6:7] offset:2048
	v_add_co_u32_e32 v4, vcc, 0xa000, v2
	s_nop 1
	v_addc_co_u32_e32 v5, vcc, 0, v3, vcc
	v_add_co_u32_e32 v6, vcc, 0xb000, v2
	s_nop 1
	v_addc_co_u32_e32 v7, vcc, 0, v3, vcc
	flat_load_dwordx2 v[122:123], v[4:5]
	flat_load_dwordx2 v[124:125], v[4:5] offset:2048
	flat_load_dwordx2 v[126:127], v[6:7]
	flat_load_dwordx2 v[128:129], v[6:7] offset:2048
	v_add_co_u32_e32 v4, vcc, 0xc000, v2
	s_nop 1
	v_addc_co_u32_e32 v5, vcc, 0, v3, vcc
	v_add_co_u32_e32 v6, vcc, 0xd000, v2
	s_nop 1
	v_addc_co_u32_e32 v7, vcc, 0, v3, vcc
	flat_load_dwordx2 v[130:131], v[4:5]
	flat_load_dwordx2 v[132:133], v[4:5] offset:2048
	flat_load_dwordx2 v[134:135], v[6:7]
	flat_load_dwordx2 v[136:137], v[6:7] offset:2048
	v_add_co_u32_e32 v4, vcc, 0xe000, v2
	s_nop 1
	v_addc_co_u32_e32 v5, vcc, 0, v3, vcc
	v_add_co_u32_e32 v2, vcc, 0xf000, v2
	s_nop 1
	v_addc_co_u32_e32 v3, vcc, 0, v3, vcc
	flat_load_dwordx2 v[138:139], v[4:5]
	flat_load_dwordx2 v[140:141], v[4:5] offset:2048
	flat_load_dwordx2 v[142:143], v[2:3]
	flat_load_dwordx2 v[144:145], v[0:1]
	v_lshlrev_b32_e32 v0, 2, v200
	v_and_b32_e32 v21, 0xfc, v0
	v_lshlrev_b32_e32 v16, 2, v21
	v_lshl_add_u64 v[8:9], s[12:13], 0, v[16:17]
	v_lshl_add_u64 v[18:19], s[14:15], 0, v[16:17]
	flat_load_dwordx4 v[0:3], v[8:9]
	flat_load_dwordx4 v[4:7], v[8:9] offset:1024
	s_nop 0
	flat_load_dwordx4 v[8:11], v[18:19]
	flat_load_dwordx4 v[12:15], v[18:19] offset:1024
	v_lshlrev_b32_e32 v18, 1, v20
	v_mov_b32_e32 v19, v80
	v_lshl_add_u64 v[18:19], s[2:3], 0, v[18:19]
	s_mov_b64 s[14:15], 0x8000000
	v_mbcnt_lo_u32_b32 v17, -1, 0
	v_lshl_add_u64 v[146:147], v[18:19], 0, s[14:15]
	s_or_b32 s15, s4, 32
	s_lshl_b32 s4, s5, 14
	v_mbcnt_hi_u32_b32 v17, -1, v17
	s_add_i32 s4, s4, 0
	v_and_b32_e32 v19, 64, v17
	v_add_u32_e32 v19, 64, v19
	v_add_u32_e32 v168, s4, v16
	v_xor_b32_e32 v16, 1, v17
	v_cmp_lt_i32_e32 vcc, v16, v19
	s_lshl_b32 s14, s5, 3
	s_mov_b64 s[4:5], 0x14000000
	v_cndmask_b32_e32 v16, v17, v16, vcc
	v_lshlrev_b32_e32 v169, 2, v16
	v_xor_b32_e32 v16, 2, v17
	v_cmp_lt_i32_e32 vcc, v16, v19
	v_ashrrev_i32_e32 v18, 3, v200
	v_and_b32_e32 v166, 0xffffffe0, v18
	v_cndmask_b32_e32 v16, v17, v16, vcc
	v_lshlrev_b32_e32 v170, 2, v16
	v_xor_b32_e32 v16, 4, v17
	v_cmp_lt_i32_e32 vcc, v16, v19
	s_mov_b32 s13, 0
	s_movk_i32 s12, 0x5000
	v_cndmask_b32_e32 v16, v17, v16, vcc
	v_lshlrev_b32_e32 v171, 2, v16
	v_xor_b32_e32 v16, 8, v17
	v_cmp_lt_i32_e32 vcc, v16, v19
	v_sub_u32_e32 v167, 0, v166
	s_nop 0
	v_cndmask_b32_e32 v16, v17, v16, vcc
	v_lshlrev_b32_e32 v172, 2, v16
	v_xor_b32_e32 v16, 16, v17
	v_cmp_lt_i32_e32 vcc, v16, v19
	s_nop 1
	v_cndmask_b32_e32 v16, v17, v16, vcc
	v_lshlrev_b32_e32 v173, 2, v16
	v_xor_b32_e32 v16, 32, v17
	v_cmp_lt_i32_e32 vcc, v16, v19
	s_nop 1
	v_cndmask_b32_e32 v16, v17, v16, vcc
	v_lshlrev_b32_e32 v174, 2, v16
	v_lshlrev_b32_e32 v16, 1, v21
	v_mov_b32_e32 v17, v80
	v_lshl_add_u64 v[16:17], s[10:11], 0, v[16:17]
	v_lshl_add_u64 v[148:149], v[16:17], 0, s[4:5]
	v_mov_b32_e32 v16, 2
	v_lshlrev_b32_sdwa v16, v16, v200 dst_sel:DWORD dst_unused:UNUSED_PAD src0_sel:DWORD src1_sel:BYTE_0
	v_mov_b32_e32 v17, v80
	v_lshl_add_u64 v[150:151], s[2:3], 0, v[16:17]
	v_mov_b32_e32 v17, 3
	v_lshlrev_b32_e32 v16, 11, v18
	v_lshlrev_b32_sdwa v17, v17, v200 dst_sel:DWORD dst_unused:UNUSED_PAD src0_sel:DWORD src1_sel:BYTE_0
	s_mov_b32 s2, 0xffff0000
	v_and_or_b32 v16, v16, s2, v17
	v_add_u32_e32 v175, 0, v16
	s_movk_i32 s10, 0x1400
	s_mov_b32 s11, 0xf800000
	s_movk_i32 s100, 0x1400
	s_mov_b32 s101, 0
	s_branch .LBB0_355

; __global__ void __launch_bounds__(NWAVES * 64, 2) mk_fwd(Args args) {
;     ...
;                     for (int i = 0; i < 30; ++i) win[i] = win[i + 8];
;     ...
;                     if (blk < 3) {
; #pragma unroll
;                         for (int i = 0; i < 8; ++i) { const bf16* zr = zb + (long)(8 * blk + 8 + i) * ZP; ru[i] = *(const unsigned*)zr; } }
.LBB0_359:
	v_mov_b32_e32 v77, v43
	v_mov_b32_e32 v76, v42
	v_mov_b32_e32 v153, v41
	v_mov_b32_e32 v152, v40
	v_mov_b32_e32 v43, v69
	v_mov_b32_e32 v42, v68
	v_mov_b32_e32 v41, v67
	v_mov_b32_e32 v40, v66
	v_mov_b64_e32 v[154:155], v[16:17]
	v_mov_b64_e32 v[156:157], v[18:19]
	v_mov_b64_e32 v[158:159], v[20:21]
	v_mov_b64_e32 v[160:161], v[22:23]
	v_mov_b64_e32 v[162:163], v[24:25]
	v_mov_b64_e32 v[164:165], v[26:27]
	v_mov_b64_e32 v[16:17], v[28:29]
	v_mov_b64_e32 v[18:19], v[30:31]
	v_mov_b64_e32 v[20:21], v[32:33]
	v_mov_b64_e32 v[22:23], v[34:35]
	v_mov_b64_e32 v[24:25], v[36:37]
	v_mov_b64_e32 v[26:27], v[38:39]
	v_mov_b64_e32 v[28:29], v[50:51]
	v_mov_b64_e32 v[30:31], v[52:53]
	v_mov_b64_e32 v[32:33], v[54:55]
	v_mov_b64_e32 v[34:35], v[56:57]
	v_mov_b64_e32 v[36:37], v[62:63]
	s_cmp_eq_u32 s2, 0x1e000
	v_mov_b64_e32 v[38:39], v[64:65]
	s_cbranch_scc1 .LBB0_358
	v_lshl_add_u64 v[50:51], v[60:61], 0, s[2:3]
	v_add_co_u32_e32 v52, vcc, 0x800a000, v50
	s_nop 1
	v_addc_co_u32_e32 v53, vcc, 0, v51, vcc
	flat_load_dword v182, v[52:53]
	v_lshl_add_u64 v[52:53], v[52:53], 0, s[100:101]
	flat_load_dword v178, v[52:53]
	v_lshl_add_u64 v[52:53], v[52:53], 0, s[100:101]
	flat_load_dword v179, v[52:53]
	v_lshl_add_u64 v[52:53], v[52:53], 0, s[100:101]
	flat_load_dword v180, v[52:53]
	v_lshl_add_u64 v[52:53], v[52:53], 0, s[100:101]
	flat_load_dword v181, v[52:53]
	v_lshl_add_u64 v[52:53], v[52:53], 0, s[100:101]
	flat_load_dword v183, v[52:53]
	v_lshl_add_u64 v[52:53], v[52:53], 0, s[100:101]
	flat_load_dword v184, v[52:53]
	v_lshl_add_u64 v[52:53], v[52:53], 0, s[100:101]
	flat_load_dword v185, v[52:53]
	s_branch .LBB0_358

;     __device__ __forceinline__ void operator()(Acc& acc, const Unit& u, int wr, int wc, int fr, int fq, PG8_LAS unsigned char* xl) const {
;     ...
;             for (int m = 0; m < 4; ++m) { const int rl = ai * HALF + wr * 64 + m * 16 + fr; const size_t off = (size_t)(u.r0 + rl) * DM + col; float s = 0.f;
; #pragma unroll
;                 for (int bj = 0; bj < 2; ++bj) {
;                     f32x4 b0, b1; unpack8(*(const u32x4*)(base + off + bj * HALF), b0, b1);
;                     const f32x4 v0 = acc[ai][bj][m][0] + b0, v1 = acc[ai][bj][m][1] + b1;
;                     acc[ai][bj][m][0] = v0; acc[ai][bj][m][1] = v1;
;                     s += (v0[0] * v0[0] + v0[1] * v0[1]) + (v0[2] * v0[2] + v0[3] * v0[3]) + (v1[0] * v1[0] + v1[1] * v1[1]) + (v1[2] * v1[2] + v1[3] * v1[3]); }
;                 s += __shfl_xor(s, 16); s += __shfl_xor(s, 32);
;                 if (fq == 0) X[rl * 4 + wc] = s; }
.LBB0_945:
	v_add_u32_e32 v144, s75, v180
	v_ashrrev_i32_e32 v145, 31, v144
	v_add_u32_e32 v146, s76, v183
	v_lshlrev_b64 v[148:149], 11, v[144:145]
	v_ashrrev_i32_e32 v147, 31, v146
	v_lshl_add_u64 v[148:149], s[18:19], 0, v[148:149]
	v_lshl_add_u64 v[152:153], v[146:147], 1, v[148:149]
	s_nop 0
	s_nop 0
	s_nop 0
	v_and_b32_e32 v157, 64, v202
	v_xor_b32_e32 v156, 16, v202
	v_add_u32_e32 v164, 64, v157
	v_cmp_lt_i32_e32 vcc, v156, v164
	s_waitcnt vmcnt(4) lgkmcnt(0)
	v_and_b32_e32 v157, 0xffff0000, v224
	v_cndmask_b32_e32 v156, v202, v156, vcc
	v_lshlrev_b32_e32 v213, 2, v156
	v_lshlrev_b32_e32 v156, 16, v224
	v_lshlrev_b32_e32 v148, 16, v225
	v_and_b32_e32 v149, 0xffff0000, v225
	v_lshlrev_b32_e32 v160, 16, v228
	v_and_b32_e32 v161, 0xffff0000, v228
	v_lshlrev_b32_e32 v152, 16, v229
	v_and_b32_e32 v153, 0xffff0000, v229
	v_lshlrev_b32_e32 v158, 16, v226
	v_and_b32_e32 v159, 0xffff0000, v226
	v_lshlrev_b32_e32 v162, 16, v230
	v_and_b32_e32 v163, 0xffff0000, v230
	v_pk_add_f32 v[126:127], v[126:127], v[148:149]
	v_pk_add_f32 v[124:125], v[124:125], v[156:157]
	v_pk_add_f32 v[118:119], v[118:119], v[152:153]
	v_pk_add_f32 v[116:117], v[116:117], v[160:161]
	v_lshlrev_b32_e32 v150, 16, v227
	v_and_b32_e32 v151, 0xffff0000, v227
	v_lshlrev_b32_e32 v154, 16, v231
	v_and_b32_e32 v155, 0xffff0000, v231
	v_add_u32_e32 v248, s75, v186
	v_ashrrev_i32_e32 v249, 31, v248
	v_lshlrev_b64 v[248:249], 10, v[248:249]
	v_lshl_add_u64 v[248:249], v[248:249], 0, v[252:253]
	v_lshl_add_u64 v[248:249], v[248:249], 1, s[18:19]
	global_load_dwordx4 v[224:227], v[248:249], off
	global_load_dwordx4 v[228:231], v[248:249], off offset:256
	v_pk_add_f32 v[120:121], v[120:121], v[158:159]
	v_pk_add_f32 v[112:113], v[112:113], v[162:163]
	v_mul_f32_e32 v148, v125, v125
	v_mul_f32_e32 v149, v127, v127
	v_mul_f32_e32 v152, v117, v117
	v_mul_f32_e32 v153, v119, v119
	v_pk_add_f32 v[122:123], v[122:123], v[150:151]
	v_pk_add_f32 v[114:115], v[114:115], v[154:155]
	v_mul_f32_e32 v150, v121, v121
	v_mul_f32_e32 v154, v113, v113
	v_fmac_f32_e32 v148, v124, v124
	v_fmac_f32_e32 v149, v126, v126
	v_fmac_f32_e32 v152, v116, v116
	v_fmac_f32_e32 v153, v118, v118
	v_mul_f32_e32 v151, v123, v123
	v_mul_f32_e32 v155, v115, v115
	v_fmac_f32_e32 v150, v120, v120
	v_fmac_f32_e32 v154, v112, v112
	v_add_f32_e32 v148, v148, v149
	v_add_f32_e32 v149, v152, v153
	v_fmac_f32_e32 v151, v122, v122
	v_fmac_f32_e32 v155, v114, v114
	v_add_f32_e32 v148, v150, v148
	v_add_f32_e32 v149, v154, v149
	v_add_f32_e32 v148, v151, v148
	v_add_f32_e32 v149, v155, v149
	v_add_f32_e32 v148, v148, v149
	v_mov_b32_e32 v149, v148
	s_nop 1
	v_permlane16_swap_b32_e32 v148, v149
	v_xor_b32_e32 v150, 32, v202
	v_cmp_lt_i32_e32 vcc, v150, v164
	s_waitcnt lgkmcnt(0)
	v_add_f32_e32 v148, v148, v149
	v_cndmask_b32_e32 v150, v202, v150, vcc
	v_lshlrev_b32_e32 v214, 2, v150
	v_mov_b32_e32 v149, v148
	s_nop 1
	v_permlane32_swap_b32_e32 v148, v149
	s_and_saveexec_b64 s[2:3], s[8:9]
	s_cbranch_execz .LBB0_947
	s_waitcnt lgkmcnt(0)
	v_add_f32_e32 v148, v148, v149
	ds_write_b32 v203, v148
.LBB0_947:
	s_or_b64 exec, exec, s[2:3]
	v_add_u32_e32 v148, s75, v184
	s_waitcnt lgkmcnt(0)
	v_ashrrev_i32_e32 v149, 31, v148
	v_lshlrev_b64 v[150:151], 11, v[148:149]
	v_lshl_add_u64 v[150:151], s[18:19], 0, v[150:151]
	v_lshl_add_u64 v[154:155], v[146:147], 1, v[150:151]
	s_nop 0
	s_nop 0
	s_nop 0
	s_waitcnt vmcnt(4) lgkmcnt(0)
	v_lshlrev_b32_e32 v158, 16, v232
	v_and_b32_e32 v159, 0xffff0000, v232
	v_lshlrev_b32_e32 v150, 16, v233
	v_and_b32_e32 v151, 0xffff0000, v233
	v_lshlrev_b32_e32 v162, 16, v236
	v_and_b32_e32 v163, 0xffff0000, v236
	v_lshlrev_b32_e32 v154, 16, v237
	v_and_b32_e32 v155, 0xffff0000, v237
	v_lshlrev_b32_e32 v160, 16, v234
	v_and_b32_e32 v161, 0xffff0000, v234
	v_lshlrev_b32_e32 v164, 16, v238
	v_and_b32_e32 v165, 0xffff0000, v238
	v_pk_add_f32 v[110:111], v[110:111], v[150:151]
	v_pk_add_f32 v[108:109], v[108:109], v[158:159]
	v_pk_add_f32 v[102:103], v[102:103], v[154:155]
	v_pk_add_f32 v[100:101], v[100:101], v[162:163]
	v_lshlrev_b32_e32 v152, 16, v235
	v_and_b32_e32 v153, 0xffff0000, v235
	v_lshlrev_b32_e32 v156, 16, v239
	v_and_b32_e32 v157, 0xffff0000, v239
	v_add_u32_e32 v248, s75, v187
	v_ashrrev_i32_e32 v249, 31, v248
	v_lshlrev_b64 v[248:249], 10, v[248:249]
	v_lshl_add_u64 v[248:249], v[248:249], 0, v[252:253]
	v_lshl_add_u64 v[248:249], v[248:249], 1, s[18:19]
	global_load_dwordx4 v[232:235], v[248:249], off
	global_load_dwordx4 v[236:239], v[248:249], off offset:256
	v_pk_add_f32 v[104:105], v[104:105], v[160:161]
	v_pk_add_f32 v[96:97], v[96:97], v[164:165]
	v_mul_f32_e32 v150, v109, v109
	v_mul_f32_e32 v151, v111, v111
	v_mul_f32_e32 v154, v101, v101
	v_mul_f32_e32 v155, v103, v103
	v_pk_add_f32 v[106:107], v[106:107], v[152:153]
	v_pk_add_f32 v[98:99], v[98:99], v[156:157]
	v_mul_f32_e32 v152, v105, v105
	v_mul_f32_e32 v156, v97, v97
	v_fmac_f32_e32 v150, v108, v108
	v_fmac_f32_e32 v151, v110, v110
	v_fmac_f32_e32 v154, v100, v100
	v_fmac_f32_e32 v155, v102, v102
	v_mul_f32_e32 v153, v107, v107
	v_mul_f32_e32 v157, v99, v99
	v_fmac_f32_e32 v152, v104, v104
	v_fmac_f32_e32 v156, v96, v96
	v_add_f32_e32 v150, v150, v151
	v_add_f32_e32 v151, v154, v155
	v_fmac_f32_e32 v153, v106, v106
	v_fmac_f32_e32 v157, v98, v98
	v_add_f32_e32 v150, v152, v150
	v_add_f32_e32 v151, v156, v151
	v_add_f32_e32 v150, v153, v150
	v_add_f32_e32 v151, v157, v151
	v_add_f32_e32 v150, v150, v151
	v_mov_b32_e32 v151, v150
	s_nop 1
	v_permlane16_swap_b32_e32 v150, v151
	s_waitcnt lgkmcnt(0)
	v_add_f32_e32 v150, v150, v151
	v_mov_b32_e32 v151, v150
	s_nop 1
	v_permlane32_swap_b32_e32 v150, v151
	s_and_saveexec_b64 s[2:3], s[8:9]
	s_cbranch_execz .LBB0_949
	s_waitcnt lgkmcnt(0)
	v_add_f32_e32 v150, v150, v151
	ds_write_b32 v204, v150
;     __device__ __forceinline__ void operator()(Acc& acc, const Unit& u, int wr, int wc, int fr, int fq, PG8_LAS unsigned char* xl) const {
;     ...
;             for (int m = 0; m < 4; ++m) { const int rl = ai * HALF + wr * 64 + m * 16 + fr; const size_t off = (size_t)(u.r0 + rl) * DM + col; float s = 0.f;
; #pragma unroll
;                 for (int bj = 0; bj < 2; ++bj) {
;                     f32x4 b0, b1; unpack8(*(const u32x4*)(base + off + bj * HALF), b0, b1);
;                     const f32x4 v0 = acc[ai][bj][m][0] + b0, v1 = acc[ai][bj][m][1] + b1;
;                     acc[ai][bj][m][0] = v0; acc[ai][bj][m][1] = v1;
;                     s += (v0[0] * v0[0] + v0[1] * v0[1]) + (v0[2] * v0[2] + v0[3] * v0[3]) + (v1[0] * v1[0] + v1[1] * v1[1]) + (v1[2] * v1[2] + v1[3] * v1[3]); }
;                 s += __shfl_xor(s, 16); s += __shfl_xor(s, 32);
;                 if (fq == 0) X[rl * 4 + wc] = s; }
.LBB0_949:
	s_or_b64 exec, exec, s[2:3]
	v_add_u32_e32 v150, s75, v185
	s_waitcnt lgkmcnt(0)
	v_ashrrev_i32_e32 v151, 31, v150
	v_lshlrev_b64 v[152:153], 11, v[150:151]
	v_lshl_add_u64 v[152:153], s[18:19], 0, v[152:153]
	v_lshl_add_u64 v[156:157], v[146:147], 1, v[152:153]
	s_nop 0
	s_nop 0
	s_nop 0
	s_waitcnt vmcnt(4) lgkmcnt(0)
	v_lshlrev_b32_e32 v160, 16, v240
	v_and_b32_e32 v161, 0xffff0000, v240
	v_lshlrev_b32_e32 v152, 16, v241
	v_and_b32_e32 v153, 0xffff0000, v241
	v_lshlrev_b32_e32 v164, 16, v244
	v_and_b32_e32 v165, 0xffff0000, v244
	v_lshlrev_b32_e32 v156, 16, v245
	v_and_b32_e32 v157, 0xffff0000, v245
	v_lshlrev_b32_e32 v162, 16, v242
	v_and_b32_e32 v163, 0xffff0000, v242
	v_lshlrev_b32_e32 v166, 16, v246
	v_and_b32_e32 v167, 0xffff0000, v246
	v_pk_add_f32 v[94:95], v[94:95], v[152:153]
	v_pk_add_f32 v[92:93], v[92:93], v[160:161]
	v_pk_add_f32 v[86:87], v[86:87], v[156:157]
	v_pk_add_f32 v[84:85], v[84:85], v[164:165]
	v_lshlrev_b32_e32 v154, 16, v243
	v_and_b32_e32 v155, 0xffff0000, v243
	v_lshlrev_b32_e32 v158, 16, v247
	v_and_b32_e32 v159, 0xffff0000, v247
	v_add_u32_e32 v248, s75, v188
	v_ashrrev_i32_e32 v249, 31, v248
	v_lshlrev_b64 v[248:249], 10, v[248:249]
	v_lshl_add_u64 v[248:249], v[248:249], 0, v[252:253]
	v_lshl_add_u64 v[248:249], v[248:249], 1, s[18:19]
	global_load_dwordx4 v[240:243], v[248:249], off
	global_load_dwordx4 v[244:247], v[248:249], off offset:256
	v_pk_add_f32 v[88:89], v[88:89], v[162:163]
	v_pk_add_f32 v[80:81], v[80:81], v[166:167]
	v_mul_f32_e32 v152, v93, v93
	v_mul_f32_e32 v153, v95, v95
	v_mul_f32_e32 v156, v85, v85
	v_mul_f32_e32 v157, v87, v87
	v_pk_add_f32 v[90:91], v[90:91], v[154:155]
	v_pk_add_f32 v[82:83], v[82:83], v[158:159]
	v_mul_f32_e32 v154, v89, v89
	v_mul_f32_e32 v158, v81, v81
	v_fmac_f32_e32 v152, v92, v92
	v_fmac_f32_e32 v153, v94, v94
	v_fmac_f32_e32 v156, v84, v84
	v_fmac_f32_e32 v157, v86, v86
	v_mul_f32_e32 v155, v91, v91
	v_mul_f32_e32 v159, v83, v83
	v_fmac_f32_e32 v154, v88, v88
	v_fmac_f32_e32 v158, v80, v80
	v_add_f32_e32 v152, v152, v153
	v_add_f32_e32 v153, v156, v157
	v_fmac_f32_e32 v155, v90, v90
	v_fmac_f32_e32 v159, v82, v82
	v_add_f32_e32 v152, v154, v152
	v_add_f32_e32 v153, v158, v153
	v_add_f32_e32 v152, v155, v152
	v_add_f32_e32 v153, v159, v153
	v_add_f32_e32 v152, v152, v153
	v_mov_b32_e32 v153, v152
	s_nop 1
	v_permlane16_swap_b32_e32 v152, v153
	s_waitcnt lgkmcnt(0)
	v_add_f32_e32 v152, v152, v153
	v_mov_b32_e32 v153, v152
	s_nop 1
	v_permlane32_swap_b32_e32 v152, v153
	s_and_saveexec_b64 s[2:3], s[8:9]
	s_cbranch_execz .LBB0_951
	s_waitcnt lgkmcnt(0)
	v_add_f32_e32 v152, v152, v153
	ds_write_b32 v205, v152
.LBB0_951:
	s_or_b64 exec, exec, s[2:3]
	v_add_u32_e32 v152, s75, v186
	s_waitcnt lgkmcnt(0)
	v_ashrrev_i32_e32 v153, 31, v152
	v_lshlrev_b64 v[154:155], 11, v[152:153]
	v_lshl_add_u64 v[154:155], s[18:19], 0, v[154:155]
	v_lshl_add_u64 v[158:159], v[146:147], 1, v[154:155]
	s_nop 0
	s_nop 0
	s_nop 0
	s_waitcnt vmcnt(4) lgkmcnt(0)
	v_lshlrev_b32_e32 v162, 16, v224
	v_and_b32_e32 v163, 0xffff0000, v224
	v_lshlrev_b32_e32 v154, 16, v225
	v_and_b32_e32 v155, 0xffff0000, v225
	v_lshlrev_b32_e32 v166, 16, v228
	v_and_b32_e32 v167, 0xffff0000, v228
	v_lshlrev_b32_e32 v158, 16, v229
	v_and_b32_e32 v159, 0xffff0000, v229
	v_lshlrev_b32_e32 v164, 16, v226
	v_and_b32_e32 v165, 0xffff0000, v226
	v_lshlrev_b32_e32 v168, 16, v230
	v_and_b32_e32 v169, 0xffff0000, v230
	v_pk_add_f32 v[78:79], v[78:79], v[154:155]
	v_pk_add_f32 v[76:77], v[76:77], v[162:163]
	v_pk_add_f32 v[70:71], v[70:71], v[158:159]
	v_pk_add_f32 v[68:69], v[68:69], v[166:167]
	v_lshlrev_b32_e32 v156, 16, v227
	v_and_b32_e32 v157, 0xffff0000, v227
	v_lshlrev_b32_e32 v160, 16, v231
	v_and_b32_e32 v161, 0xffff0000, v231
	v_add_u32_e32 v248, s75, v189
	v_ashrrev_i32_e32 v249, 31, v248
	v_lshlrev_b64 v[248:249], 10, v[248:249]
	v_lshl_add_u64 v[248:249], v[248:249], 0, v[252:253]
	v_lshl_add_u64 v[248:249], v[248:249], 1, s[18:19]
	global_load_dwordx4 v[224:227], v[248:249], off
	global_load_dwordx4 v[228:231], v[248:249], off offset:256
	v_pk_add_f32 v[72:73], v[72:73], v[164:165]
	v_pk_add_f32 v[64:65], v[64:65], v[168:169]
	v_mul_f32_e32 v154, v77, v77
	v_mul_f32_e32 v155, v79, v79
	v_mul_f32_e32 v158, v69, v69
	v_mul_f32_e32 v159, v71, v71
	v_pk_add_f32 v[74:75], v[74:75], v[156:157]
	v_pk_add_f32 v[66:67], v[66:67], v[160:161]
	v_mul_f32_e32 v156, v73, v73
	v_mul_f32_e32 v160, v65, v65
	v_fmac_f32_e32 v154, v76, v76
	v_fmac_f32_e32 v155, v78, v78
	v_fmac_f32_e32 v158, v68, v68
	v_fmac_f32_e32 v159, v70, v70
	v_mul_f32_e32 v157, v75, v75
	v_mul_f32_e32 v161, v67, v67
	v_fmac_f32_e32 v156, v72, v72
	v_fmac_f32_e32 v160, v64, v64
	v_add_f32_e32 v154, v154, v155
	v_add_f32_e32 v155, v158, v159
	v_fmac_f32_e32 v157, v74, v74
	v_fmac_f32_e32 v161, v66, v66
	v_add_f32_e32 v154, v156, v154
	v_add_f32_e32 v155, v160, v155
	v_add_f32_e32 v154, v157, v154
	v_add_f32_e32 v155, v161, v155
	v_add_f32_e32 v154, v154, v155
	v_mov_b32_e32 v155, v154
	s_nop 1
	v_permlane16_swap_b32_e32 v154, v155
	s_waitcnt lgkmcnt(0)
	v_add_f32_e32 v154, v154, v155
	v_mov_b32_e32 v155, v154
	s_nop 1
	v_permlane32_swap_b32_e32 v154, v155
	s_and_saveexec_b64 s[2:3], s[8:9]
	s_cbranch_execz .LBB0_953
	s_waitcnt lgkmcnt(0)
	v_add_f32_e32 v154, v154, v155
	ds_write_b32 v206, v154
;     __device__ __forceinline__ void operator()(Acc& acc, const Unit& u, int wr, int wc, int fr, int fq, PG8_LAS unsigned char* xl) const {
;     ...
;             for (int m = 0; m < 4; ++m) { const int rl = ai * HALF + wr * 64 + m * 16 + fr; const size_t off = (size_t)(u.r0 + rl) * DM + col; float s = 0.f;
; #pragma unroll
;                 for (int bj = 0; bj < 2; ++bj) {
;                     f32x4 b0, b1; unpack8(*(const u32x4*)(base + off + bj * HALF), b0, b1);
;                     const f32x4 v0 = acc[ai][bj][m][0] + b0, v1 = acc[ai][bj][m][1] + b1;
;                     acc[ai][bj][m][0] = v0; acc[ai][bj][m][1] = v1;
;                     s += (v0[0] * v0[0] + v0[1] * v0[1]) + (v0[2] * v0[2] + v0[3] * v0[3]) + (v1[0] * v1[0] + v1[1] * v1[1]) + (v1[2] * v1[2] + v1[3] * v1[3]); }
;                 s += __shfl_xor(s, 16); s += __shfl_xor(s, 32);
;                 if (fq == 0) X[rl * 4 + wc] = s; }
.LBB0_953:
	s_or_b64 exec, exec, s[2:3]
	v_add_u32_e32 v154, s75, v187
	s_waitcnt lgkmcnt(0)
	v_ashrrev_i32_e32 v155, 31, v154
	v_lshlrev_b64 v[156:157], 11, v[154:155]
	v_lshl_add_u64 v[156:157], s[18:19], 0, v[156:157]
	v_lshl_add_u64 v[160:161], v[146:147], 1, v[156:157]
	s_nop 0
	s_nop 0
	s_nop 0
	s_waitcnt vmcnt(4) lgkmcnt(0)
	v_lshlrev_b32_e32 v164, 16, v232
	v_and_b32_e32 v165, 0xffff0000, v232
	v_lshlrev_b32_e32 v156, 16, v233
	v_and_b32_e32 v157, 0xffff0000, v233
	v_lshlrev_b32_e32 v168, 16, v236
	v_and_b32_e32 v169, 0xffff0000, v236
	v_lshlrev_b32_e32 v160, 16, v237
	v_and_b32_e32 v161, 0xffff0000, v237
	v_lshlrev_b32_e32 v166, 16, v234
	v_and_b32_e32 v167, 0xffff0000, v234
	v_lshlrev_b32_e32 v170, 16, v238
	v_and_b32_e32 v171, 0xffff0000, v238
	v_pk_add_f32 v[62:63], v[62:63], v[156:157]
	v_pk_add_f32 v[60:61], v[60:61], v[164:165]
	v_pk_add_f32 v[54:55], v[54:55], v[160:161]
	v_pk_add_f32 v[52:53], v[52:53], v[168:169]
	v_lshlrev_b32_e32 v158, 16, v235
	v_and_b32_e32 v159, 0xffff0000, v235
	v_lshlrev_b32_e32 v162, 16, v239
	v_and_b32_e32 v163, 0xffff0000, v239
	v_add_u32_e32 v248, s75, v190
	v_ashrrev_i32_e32 v249, 31, v248
	v_lshlrev_b64 v[248:249], 10, v[248:249]
	v_lshl_add_u64 v[248:249], v[248:249], 0, v[252:253]
	v_lshl_add_u64 v[248:249], v[248:249], 1, s[18:19]
	global_load_dwordx4 v[232:235], v[248:249], off
	global_load_dwordx4 v[236:239], v[248:249], off offset:256
	v_pk_add_f32 v[56:57], v[56:57], v[166:167]
	v_pk_add_f32 v[48:49], v[48:49], v[170:171]
	v_mul_f32_e32 v156, v61, v61
	v_mul_f32_e32 v157, v63, v63
	v_mul_f32_e32 v160, v53, v53
	v_mul_f32_e32 v161, v55, v55
	v_pk_add_f32 v[58:59], v[58:59], v[158:159]
	v_pk_add_f32 v[50:51], v[50:51], v[162:163]
	v_mul_f32_e32 v158, v57, v57
	v_mul_f32_e32 v162, v49, v49
	v_fmac_f32_e32 v156, v60, v60
	v_fmac_f32_e32 v157, v62, v62
	v_fmac_f32_e32 v160, v52, v52
	v_fmac_f32_e32 v161, v54, v54
	v_mul_f32_e32 v159, v59, v59
	v_mul_f32_e32 v163, v51, v51
	v_fmac_f32_e32 v158, v56, v56
	v_fmac_f32_e32 v162, v48, v48
	v_add_f32_e32 v156, v156, v157
	v_add_f32_e32 v157, v160, v161
	v_fmac_f32_e32 v159, v58, v58
	v_fmac_f32_e32 v163, v50, v50
	v_add_f32_e32 v156, v158, v156
	v_add_f32_e32 v157, v162, v157
	v_add_f32_e32 v156, v159, v156
	v_add_f32_e32 v157, v163, v157
	v_add_f32_e32 v156, v156, v157
	v_mov_b32_e32 v157, v156
	s_nop 1
	v_permlane16_swap_b32_e32 v156, v157
	s_waitcnt lgkmcnt(0)
	v_add_f32_e32 v156, v156, v157
	v_mov_b32_e32 v157, v156
	s_nop 1
	v_permlane32_swap_b32_e32 v156, v157
	s_and_saveexec_b64 s[2:3], s[8:9]
	s_cbranch_execz .LBB0_955
	s_waitcnt lgkmcnt(0)
	v_add_f32_e32 v156, v156, v157
	ds_write_b32 v207, v156
.LBB0_955:
	s_or_b64 exec, exec, s[2:3]
	v_add_u32_e32 v156, s75, v188
	s_waitcnt lgkmcnt(0)
	v_ashrrev_i32_e32 v157, 31, v156
	v_lshlrev_b64 v[158:159], 11, v[156:157]
	v_lshl_add_u64 v[158:159], s[18:19], 0, v[158:159]
	v_lshl_add_u64 v[162:163], v[146:147], 1, v[158:159]
	s_nop 0
	s_nop 0
	s_nop 0
	s_waitcnt vmcnt(4) lgkmcnt(0)
	v_lshlrev_b32_e32 v166, 16, v240
	v_and_b32_e32 v167, 0xffff0000, v240
	v_lshlrev_b32_e32 v158, 16, v241
	v_and_b32_e32 v159, 0xffff0000, v241
	v_lshlrev_b32_e32 v170, 16, v244
	v_and_b32_e32 v171, 0xffff0000, v244
	v_lshlrev_b32_e32 v162, 16, v245
	v_and_b32_e32 v163, 0xffff0000, v245
	v_lshlrev_b32_e32 v168, 16, v242
	v_and_b32_e32 v169, 0xffff0000, v242
	v_lshlrev_b32_e32 v172, 16, v246
	v_and_b32_e32 v173, 0xffff0000, v246
	v_pk_add_f32 v[46:47], v[46:47], v[158:159]
	v_pk_add_f32 v[44:45], v[44:45], v[166:167]
	v_pk_add_f32 v[38:39], v[38:39], v[162:163]
	v_pk_add_f32 v[36:37], v[36:37], v[170:171]
	v_lshlrev_b32_e32 v160, 16, v243
	v_and_b32_e32 v161, 0xffff0000, v243
	v_lshlrev_b32_e32 v164, 16, v247
	v_and_b32_e32 v165, 0xffff0000, v247
	v_pk_add_f32 v[40:41], v[40:41], v[168:169]
	v_pk_add_f32 v[32:33], v[32:33], v[172:173]
	v_mul_f32_e32 v158, v45, v45
	v_mul_f32_e32 v159, v47, v47
	v_mul_f32_e32 v162, v37, v37
	v_mul_f32_e32 v163, v39, v39
	v_pk_add_f32 v[42:43], v[42:43], v[160:161]
	v_pk_add_f32 v[34:35], v[34:35], v[164:165]
	v_mul_f32_e32 v160, v41, v41
	v_mul_f32_e32 v164, v33, v33
	v_fmac_f32_e32 v158, v44, v44
	v_fmac_f32_e32 v159, v46, v46
	v_fmac_f32_e32 v162, v36, v36
	v_fmac_f32_e32 v163, v38, v38
	v_mul_f32_e32 v161, v43, v43
	v_mul_f32_e32 v165, v35, v35
	v_fmac_f32_e32 v160, v40, v40
	v_fmac_f32_e32 v164, v32, v32
	v_add_f32_e32 v158, v158, v159
	v_add_f32_e32 v159, v162, v163
	v_fmac_f32_e32 v161, v42, v42
	v_fmac_f32_e32 v165, v34, v34
	v_add_f32_e32 v158, v160, v158
	v_add_f32_e32 v159, v164, v159
	v_add_f32_e32 v158, v161, v158
	v_add_f32_e32 v159, v165, v159
	v_add_f32_e32 v158, v158, v159
	v_mov_b32_e32 v159, v158
	s_nop 1
	v_permlane16_swap_b32_e32 v158, v159
	s_waitcnt lgkmcnt(0)
	v_add_f32_e32 v158, v158, v159
	v_mov_b32_e32 v159, v158
	s_nop 1
	v_permlane32_swap_b32_e32 v158, v159
	s_and_saveexec_b64 s[2:3], s[8:9]
	s_cbranch_execz .LBB0_957
	s_waitcnt lgkmcnt(0)
	v_add_f32_e32 v158, v158, v159
	ds_write_b32 v208, v158
;     __device__ __forceinline__ void operator()(Acc& acc, const Unit& u, int wr, int wc, int fr, int fq, PG8_LAS unsigned char* xl) const {
;     ...
;             for (int m = 0; m < 4; ++m) { const int rl = ai * HALF + wr * 64 + m * 16 + fr; const size_t off = (size_t)(u.r0 + rl) * DM + col; float s = 0.f;
; #pragma unroll
;                 for (int bj = 0; bj < 2; ++bj) {
;                     f32x4 b0, b1; unpack8(*(const u32x4*)(base + off + bj * HALF), b0, b1);
;                     const f32x4 v0 = acc[ai][bj][m][0] + b0, v1 = acc[ai][bj][m][1] + b1;
;                     acc[ai][bj][m][0] = v0; acc[ai][bj][m][1] = v1;
;                     s += (v0[0] * v0[0] + v0[1] * v0[1]) + (v0[2] * v0[2] + v0[3] * v0[3]) + (v1[0] * v1[0] + v1[1] * v1[1]) + (v1[2] * v1[2] + v1[3] * v1[3]); }
;                 s += __shfl_xor(s, 16); s += __shfl_xor(s, 32);
;                 if (fq == 0) X[rl * 4 + wc] = s; }
.LBB0_957:
	s_or_b64 exec, exec, s[2:3]
	v_add_u32_e32 v158, s75, v189
	s_waitcnt lgkmcnt(0)
	v_ashrrev_i32_e32 v159, 31, v158
	v_lshlrev_b64 v[160:161], 11, v[158:159]
	v_lshl_add_u64 v[160:161], s[18:19], 0, v[160:161]
	v_lshl_add_u64 v[164:165], v[146:147], 1, v[160:161]
	s_nop 0
	s_nop 0
	s_nop 0
	s_waitcnt vmcnt(2) lgkmcnt(0)
	v_lshlrev_b32_e32 v168, 16, v224
	v_and_b32_e32 v169, 0xffff0000, v224
	v_lshlrev_b32_e32 v160, 16, v225
	v_and_b32_e32 v161, 0xffff0000, v225
	v_lshlrev_b32_e32 v172, 16, v228
	v_and_b32_e32 v173, 0xffff0000, v228
	v_lshlrev_b32_e32 v164, 16, v229
	v_and_b32_e32 v165, 0xffff0000, v229
	v_lshlrev_b32_e32 v170, 16, v226
	v_and_b32_e32 v171, 0xffff0000, v226
	v_lshlrev_b32_e32 v174, 16, v230
	v_and_b32_e32 v175, 0xffff0000, v230
	v_pk_add_f32 v[30:31], v[30:31], v[160:161]
	v_pk_add_f32 v[28:29], v[28:29], v[168:169]
	v_pk_add_f32 v[22:23], v[22:23], v[164:165]
	v_pk_add_f32 v[20:21], v[20:21], v[172:173]
	v_lshlrev_b32_e32 v162, 16, v227
	v_and_b32_e32 v163, 0xffff0000, v227
	v_lshlrev_b32_e32 v166, 16, v231
	v_and_b32_e32 v167, 0xffff0000, v231
	v_pk_add_f32 v[24:25], v[24:25], v[170:171]
	v_pk_add_f32 v[16:17], v[16:17], v[174:175]
	v_mul_f32_e32 v160, v29, v29
	v_mul_f32_e32 v161, v31, v31
	v_mul_f32_e32 v164, v21, v21
	v_mul_f32_e32 v165, v23, v23
	v_pk_add_f32 v[26:27], v[26:27], v[162:163]
	v_pk_add_f32 v[18:19], v[18:19], v[166:167]
	v_mul_f32_e32 v162, v25, v25
	v_mul_f32_e32 v166, v17, v17
	v_fmac_f32_e32 v160, v28, v28
	v_fmac_f32_e32 v161, v30, v30
	v_fmac_f32_e32 v164, v20, v20
	v_fmac_f32_e32 v165, v22, v22
	v_mul_f32_e32 v163, v27, v27
	v_mul_f32_e32 v167, v19, v19
	v_fmac_f32_e32 v162, v24, v24
	v_fmac_f32_e32 v166, v16, v16
	v_add_f32_e32 v160, v160, v161
	v_add_f32_e32 v161, v164, v165
	v_fmac_f32_e32 v163, v26, v26
	v_fmac_f32_e32 v167, v18, v18
	v_add_f32_e32 v160, v162, v160
	v_add_f32_e32 v161, v166, v161
	v_add_f32_e32 v160, v163, v160
	v_add_f32_e32 v161, v167, v161
	v_add_f32_e32 v160, v160, v161
	v_mov_b32_e32 v161, v160
	s_nop 1
	v_permlane16_swap_b32_e32 v160, v161
	s_waitcnt lgkmcnt(0)
	v_add_f32_e32 v160, v160, v161
	v_mov_b32_e32 v161, v160
	s_nop 1
	v_permlane32_swap_b32_e32 v160, v161
	s_and_saveexec_b64 s[2:3], s[8:9]
	s_cbranch_execz .LBB0_959
	s_waitcnt lgkmcnt(0)
	v_add_f32_e32 v160, v160, v161
	ds_write_b32 v209, v160
.LBB0_959:
	s_or_b64 exec, exec, s[2:3]
	v_add_u32_e32 v160, s75, v190
	s_waitcnt lgkmcnt(0)
	v_ashrrev_i32_e32 v161, 31, v160
	v_lshlrev_b64 v[162:163], 11, v[160:161]
	v_lshl_add_u64 v[162:163], s[18:19], 0, v[162:163]
	v_lshl_add_u64 v[166:167], v[146:147], 1, v[162:163]
	s_nop 0
	s_nop 0
	s_nop 0
	s_waitcnt vmcnt(0) lgkmcnt(0)
	v_lshlrev_b32_e32 v170, 16, v232
	v_and_b32_e32 v171, 0xffff0000, v232
	v_lshlrev_b32_e32 v162, 16, v233
	v_and_b32_e32 v163, 0xffff0000, v233
	v_lshlrev_b32_e32 v216, 16, v236
	v_and_b32_e32 v217, 0xffff0000, v236
	v_lshlrev_b32_e32 v166, 16, v237
	v_and_b32_e32 v167, 0xffff0000, v237
	v_lshlrev_b32_e32 v172, 16, v234
	v_and_b32_e32 v173, 0xffff0000, v234
	v_lshlrev_b32_e32 v164, 16, v235
	v_and_b32_e32 v165, 0xffff0000, v235
	v_lshlrev_b32_e32 v218, 16, v238
	v_and_b32_e32 v219, 0xffff0000, v238
	v_lshlrev_b32_e32 v222, 16, v239
	v_and_b32_e32 v223, 0xffff0000, v239
	v_pk_add_f32 v[174:175], v[14:15], v[162:163]
	v_pk_add_f32 v[176:177], v[12:13], v[170:171]
	v_pk_add_f32 v[166:167], v[6:7], v[166:167]
	v_pk_add_f32 v[168:169], v[4:5], v[216:217]
	v_pk_add_f32 v[170:171], v[10:11], v[164:165]
	v_pk_add_f32 v[172:173], v[8:9], v[172:173]
	v_pk_add_f32 v[164:165], v[0:1], v[218:219]
	v_mul_f32_e32 v0, v177, v177
	v_mul_f32_e32 v1, v175, v175
	v_mul_f32_e32 v4, v169, v169
	v_mul_f32_e32 v5, v167, v167
	v_pk_add_f32 v[162:163], v[2:3], v[222:223]
	v_mul_f32_e32 v2, v173, v173
	v_mul_f32_e32 v6, v165, v165
	v_fmac_f32_e32 v0, v176, v176
	v_fmac_f32_e32 v1, v174, v174
	v_fmac_f32_e32 v4, v168, v168
	v_fmac_f32_e32 v5, v166, v166
	v_mul_f32_e32 v3, v171, v171
	v_mul_f32_e32 v7, v163, v163
	v_fmac_f32_e32 v2, v172, v172
	v_fmac_f32_e32 v6, v164, v164
	v_add_f32_e32 v0, v0, v1
	v_add_f32_e32 v1, v4, v5
	v_fmac_f32_e32 v3, v170, v170
	v_fmac_f32_e32 v7, v162, v162
	v_add_f32_e32 v0, v2, v0
	v_add_f32_e32 v1, v6, v1
	v_add_f32_e32 v0, v3, v0
	v_add_f32_e32 v1, v7, v1
	v_add_f32_e32 v0, v0, v1
	v_mov_b32_e32 v1, v0
	s_nop 1
	v_permlane16_swap_b32_e32 v0, v1
	s_waitcnt lgkmcnt(0)
	v_add_f32_e32 v0, v0, v1
	v_mov_b32_e32 v1, v0
	s_nop 1
	v_permlane32_swap_b32_e32 v0, v1
	s_and_saveexec_b64 s[2:3], s[8:9]
	s_cbranch_execz .LBB0_961
	s_waitcnt lgkmcnt(0)
	v_add_f32_e32 v0, v0, v1
	ds_write_b32 v210, v0
